# v6 + mixer-A sink logit load hoisted from unit epilogue to unit prologue
# baseline (speedup 1.0000x reference)
; #define LAS __attribute__((address_space(3)))
; template <int MODE, bool FIX> ...
;     ...
;         const int qblk = rem >> 1, kvh = rem & 1, q0 = qblk * 64;
;         head = kvh * 4 + (wid >> 1); s_sub = wid & 1; qtok = q0 + 32 * s_sub + r32; qcol = head * 64; kcol = 512 + kvh * 64; vcol = 640 + kvh * 64; ocol = head * 64;
;         tl0 = (2 - qblk) > 0 ? (2 - qblk) : 0; const int tl1 = (65 - qblk) < 4 ? (65 - qblk) : 4; NTL = tl1 - tl0 + 1; lrow0 = b * SEQ + q0 - 128 + 64 * tl0;
;     } else {
;         head = rem >> 4; const int r0 = 4 * (rem & 15), rp = wid >> 2, cgp = wid & 3;
;         qrow = r0 + 2 * rp + (r32 >> 4); qc = 16 * cgp + (r32 & 15); qtok = qrow * 64 + qc; qcol = 768 + head * 64; kcol = 1280 + head * 64; vcol = 1792 + head * 64; ocol = 512 + head * 64;
;         kr_lo = (r0 - 4) > 0 ? (r0 - 4) : 0; const int kr_hi = clampi(r0 - 1, 0, 56) + 7; NTL = kr_hi - kr_lo + 1; lrow0 = b * SEQ + kr_lo * 64;
;         kc0 = clampi(16 * cgp - 8, 0, 32); const int cs = clampi(qc - 8, 0, 48);
;         wa_lo = clampi(r0 + 2 * rp - 4, 0, 56); wa_hi = clampi(r0 + 2 * rp - 3, 0, 56) + 7; rs = clampi(qrow - 4, 0, 56);
; #pragma unroll
;         for (int r = 0; r < 16; ++r) { const int kc = kc0 + (r & 3) + 8 * (r >> 2) + 4 * hi; if ((unsigned)(kc - cs) < 16u) colmask |= (1u << r); }
;         LAS float* rt = (LAS float*)(lds + RPB_OFF);
;         if (tid < 465) rt[tid] = rpb[head * 465 + tid] * LOG2E;
;     }
;     const int NT = NTL + 4, crow0 = ML + b * CTXL;
;     const LAS float* rpbl = (const LAS float*)(lds + RPB_OFF);
;     bf16x8 qf[4];
;     { const bf16_t* qp = QKV + (size_t)(b * SEQ + qtok) * INC + qcol + hi * 8;
; #pragma unroll
;       for (int d0 = 0; d0 < 4; ++d0) qf[d0] = *(const bf16x8*)(qp + d0 * 16); }
;     float m = FIX ? Mb : -INFINITY, l = 0.f;
;     const float ci = FIX ? -Mb : 0.f;
;     const f32x16 cinit = {ci, ci, ci, ci, ci, ci, ci, ci, ci, ci, ci, ci, ci, ci, ci, ci};
;     f32x16 o0 = {0.f, 0.f, 0.f, 0.f, 0.f, 0.f, 0.f, 0.f, 0.f, 0.f, 0.f, 0.f, 0.f, 0.f, 0.f, 0.f}, o1 = o0;
;     ...
;     if (MODE == 0) lt += __builtin_amdgcn_exp2f(sinkp[head] * LOG2E - m);
.LBB0_655:
	s_and_b64 vcc, exec, s[70:71]
	s_cbranch_vccz .LBB0_572
	v_readlane_b32 s2, v255, 5
	v_readlane_b32 s3, v255, 6
	s_lshl_b32 s0, s93, 2
	v_mov_b32_e32 v243, s0
	s_nop 4
	global_load_dword v243, v243, s[2:3]
	v_readlane_b32 s2, v255, 20
	s_lshl_b32 s78, s75, 12
	v_readlane_b32 s3, v255, 21
	v_or_b32_e32 v128, s78, v225
	s_or_b32 s77, s83, s78
	v_mov_b64_e32 v[2:3], s[2:3]
	s_movk_i32 s2, 0x1200
	s_lshl_b32 s1, s75, 8
	v_mad_i64_i32 v[2:3], s[2:3], v128, s2, v[2:3]
	s_sub_i32 s53, 0x41, s72
	s_add_i32 s0, s77, 0xffffff80
	s_lshl_b32 s86, s81, 1
	s_add_i32 s1, s1, 0x8000
	s_lshl_b32 s2, s97, 7
	s_mov_b32 s3, s87
	s_cmp_lt_u32 s72, 62
	v_lshl_add_u64 v[130:131], v[180:181], 0, s[2:3]
	s_cselect_b64 s[2:3], -1, 0
	s_cmp_gt_u32 s72, 1
	s_cselect_b64 s[88:89], -1, 0
	v_cndmask_b32_e64 v0, 0, 1, s[2:3]
	s_and_b64 s[2:3], s[88:89], exec
	s_cselect_b32 s52, 0, 0x100
	v_readfirstlane_b32 s2, v0
	s_cmp_lg_u64 s[88:89], 0
	s_addc_u32 s2, s2, 0
	s_max_i32 s72, s90, 1
	s_min_u32 s3, s53, 3
	s_sub_i32 s3, s3, s72
	s_lshl_b32 s70, s72, 6
	v_lshl_add_u64 v[2:3], v[2:3], 0, s[86:87]
	s_cmp_eq_u32 s2, 0
	v_lshl_add_u64 v[2:3], v[176:177], 1, v[2:3]
	s_cselect_b32 s52, s70, s52
	global_load_dwordx4 v[92:95], v[2:3], off
	global_load_dwordx4 v[96:99], v[2:3], off offset:32
	global_load_dwordx4 v[100:103], v[2:3], off offset:64
	global_load_dwordx4 v[104:107], v[2:3], off offset:96
	s_add_i32 s52, s52, s0
	v_mad_i64_i32 v[2:3], s[70:71], s52, v221, v[130:131]
	global_load_dwordx4 v[108:111], v[2:3], off offset:1024
	global_load_dwordx4 v[112:115], v[2:3], off offset:1280
	s_cmp_lg_u32 s2, 0
	s_mov_b64 s[70:71], -1
	s_cbranch_scc0 .LBB0_660
	s_max_i32 s52, s80, 1
	s_add_i32 s52, s52, s91
	s_lshl_b32 s70, s52, 6
	s_add_i32 s78, s78, s70
	s_lshl_b32 s70, s2, 6
	s_sub_i32 s70, s78, s70
	v_mov_b32_e32 v150, 0
	s_waitcnt vmcnt(1)
	v_mov_b64_e32 v[2:3], v[108:109]
	s_waitcnt vmcnt(0)
	v_mov_b64_e32 v[6:7], v[112:113]
	s_sub_i32 s52, s72, s2
	s_add_i32 s75, s77, 0x80
	s_add_i32 s77, s2, s3
	s_sub_i32 s78, s70, 64
	s_mov_b32 s79, 0
	v_mov_b64_e32 v[4:5], v[110:111]
	v_mov_b64_e32 v[8:9], v[114:115]
	s_mov_b32 s70, 0
	v_mov_b32_e32 v32, 0
	v_mov_b32_e32 v33, v150
	v_mov_b32_e32 v34, v150
	v_mov_b32_e32 v35, v150
	v_mov_b32_e32 v36, v150
	v_mov_b32_e32 v37, v150
	v_mov_b32_e32 v38, v150
	v_mov_b32_e32 v39, v150
	v_mov_b32_e32 v40, v150
	v_mov_b32_e32 v41, v150
	v_mov_b32_e32 v42, v150
	v_mov_b32_e32 v43, v150
	v_mov_b32_e32 v44, v150
	v_mov_b32_e32 v45, v150
	v_mov_b32_e32 v46, v150
	v_mov_b32_e32 v47, v150
	v_mov_b32_e32 v48, 0
	v_mov_b32_e32 v49, v150
	v_mov_b32_e32 v50, v150
	v_mov_b32_e32 v51, v150
	v_mov_b32_e32 v52, v150
	v_mov_b32_e32 v53, v150
	v_mov_b32_e32 v54, v150
	v_mov_b32_e32 v55, v150
	v_mov_b32_e32 v56, v150
	v_mov_b32_e32 v57, v150
	v_mov_b32_e32 v58, v150
	v_mov_b32_e32 v59, v150
	v_mov_b32_e32 v60, v150
	v_mov_b32_e32 v61, v150
	v_mov_b32_e32 v62, v150
	v_mov_b32_e32 v63, v150

; __device__ __forceinline__ float swap_sum(float v) { auto rr = __builtin_amdgcn_permlane32_swap(__float_as_uint(v), __float_as_uint(v), false, false); return __uint_as_float(rr[0]) + __uint_as_float(rr[1]); }
; template <int MODE, bool FIX> ...
;     ...
;     float lt = swap_sum(l);
;     if (MODE == 0) lt += __builtin_amdgcn_exp2f(sinkp[head] * LOG2E - m);
;     const float inv = 1.0f / lt;
;     float ss = 0.f;
; #pragma unroll
;     for (int r = 0; r < 16; ++r) { o0[r] *= inv; o1[r] *= inv; ss += o0[r] * o0[r] + o1[r] * o1[r]; }
;     ss = swap_sum(ss);
;     const size_t orow = (size_t)(b * SEQ + qtok);
;     if (hi == 0) atomicAdd(ssq1 + 2 * orow + MODE, ss);
.LBB0_672:
	s_lshl_b32 s0, s93, 2
	v_mov_b32_e32 v0, s0
	v_readlane_b32 s0, v255, 5
	v_readlane_b32 s1, v255, 6
	s_waitcnt vmcnt(1)
	v_mov_b32_e32 v2, v150
	s_nop 1
	v_permlane32_swap_b32_e32 v150, v2
	v_add_f32_e32 v2, v150, v2
	s_mov_b32 s0, 0x3fb8aa3b
	s_waitcnt vmcnt(0)
	v_fma_f32 v0, v243, s0, -v182
	v_exp_f32_e32 v0, v0
	s_nop 0
	v_add_f32_e32 v0, v2, v0
	v_div_scale_f32 v2, s[0:1], v0, v0, 1.0
	v_rcp_f32_e32 v3, v2
	v_div_scale_f32 v4, vcc, 1.0, v0, 1.0
	v_fma_f32 v5, -v2, v3, 1.0
	v_fmac_f32_e32 v3, v5, v3
	v_mul_f32_e32 v5, v4, v3
	v_fma_f32 v6, -v2, v5, v4
	v_fmac_f32_e32 v5, v6, v3
	v_fma_f32 v2, -v2, v5, v4
	v_div_fmas_f32 v2, v2, v3, v5
	v_div_fixup_f32 v0, v2, v0, 1.0
	v_pk_mul_f32 v[2:3], v[48:49], v[0:1] op_sel_hi:[1,0]
	v_pk_mul_f32 v[4:5], v[32:33], v[0:1] op_sel_hi:[1,0]
	v_pk_mul_f32 v[6:7], v[50:51], v[0:1] op_sel_hi:[1,0]
	v_pk_mul_f32 v[50:51], v[2:3], v[2:3]
	v_pk_mul_f32 v[8:9], v[34:35], v[0:1] op_sel_hi:[1,0]
	v_pk_mul_f32 v[14:15], v[52:53], v[0:1] op_sel_hi:[1,0]
	v_pk_mul_f32 v[52:53], v[6:7], v[6:7]
	v_pk_fma_f32 v[50:51], v[4:5], v[4:5], v[50:51]
	v_pk_fma_f32 v[52:53], v[8:9], v[8:9], v[52:53]
	v_pk_add_f32 v[50:51], v[50:51], v[50:51] op_sel:[0,1] op_sel_hi:[1,0]
	v_pk_mul_f32 v[32:33], v[36:37], v[0:1] op_sel_hi:[1,0]
	v_pk_mul_f32 v[48:49], v[38:39], v[0:1] op_sel_hi:[1,0]
	v_pk_mul_f32 v[38:39], v[54:55], v[0:1] op_sel_hi:[1,0]
	v_pk_mul_f32 v[54:55], v[14:15], v[14:15]
	v_pk_add_f32 v[50:51], v[52:53], v[50:51]
	v_pk_fma_f32 v[54:55], v[32:33], v[32:33], v[54:55]
	v_pk_add_f32 v[50:51], v[52:53], v[50:51] op_sel:[1,0] op_sel_hi:[0,1]
	v_pk_mul_f32 v[10:11], v[56:57], v[0:1] op_sel_hi:[1,0]
	v_pk_mul_f32 v[56:57], v[38:39], v[38:39]
	v_pk_add_f32 v[50:51], v[54:55], v[50:51]
	v_pk_fma_f32 v[56:57], v[48:49], v[48:49], v[56:57]
	v_pk_add_f32 v[50:51], v[54:55], v[50:51] op_sel:[1,0] op_sel_hi:[0,1]
	v_pk_mul_f32 v[12:13], v[40:41], v[0:1] op_sel_hi:[1,0]
	v_pk_mul_f32 v[34:35], v[58:59], v[0:1] op_sel_hi:[1,0]
	v_pk_mul_f32 v[58:59], v[10:11], v[10:11]
	v_pk_add_f32 v[50:51], v[56:57], v[50:51]
	v_pk_fma_f32 v[58:59], v[12:13], v[12:13], v[58:59]
	v_pk_add_f32 v[50:51], v[56:57], v[50:51] op_sel:[1,0] op_sel_hi:[0,1]
	v_pk_mul_f32 v[36:37], v[42:43], v[0:1] op_sel_hi:[1,0]
	v_pk_mul_f32 v[40:41], v[60:61], v[0:1] op_sel_hi:[1,0]
	v_pk_mul_f32 v[60:61], v[34:35], v[34:35]
	v_pk_add_f32 v[50:51], v[58:59], v[50:51]
	v_pk_fma_f32 v[60:61], v[36:37], v[36:37], v[60:61]
	v_pk_add_f32 v[50:51], v[58:59], v[50:51] op_sel:[1,0] op_sel_hi:[0,1]
	v_pk_mul_f32 v[42:43], v[44:45], v[0:1] op_sel_hi:[1,0]
	v_pk_mul_f32 v[44:45], v[62:63], v[0:1] op_sel_hi:[1,0]
	v_pk_mul_f32 v[62:63], v[40:41], v[40:41]
	v_pk_add_f32 v[50:51], v[60:61], v[50:51]
	v_pk_fma_f32 v[62:63], v[42:43], v[42:43], v[62:63]
	v_pk_add_f32 v[50:51], v[60:61], v[50:51] op_sel:[1,0] op_sel_hi:[0,1]
	v_pk_mul_f32 v[46:47], v[46:47], v[0:1] op_sel_hi:[1,0]
	v_pk_mul_f32 v[64:65], v[44:45], v[44:45]
	v_pk_add_f32 v[50:51], v[62:63], v[50:51]
	v_pk_fma_f32 v[64:65], v[46:47], v[46:47], v[64:65]
	v_pk_add_f32 v[50:51], v[62:63], v[50:51] op_sel:[1,0] op_sel_hi:[0,1]
	v_pk_add_f32 v[50:51], v[64:65], v[50:51]
	s_nop 0
	v_pk_add_f32 v[52:53], v[64:65], v[50:51] op_sel:[1,0] op_sel_hi:[0,1]
	v_mov_b32_e32 v0, v52
	s_nop 1
	v_permlane32_swap_b32_e32 v52, v0
	v_mov_b64_e32 v[50:51], 8
	s_mov_b64 s[70:71], exec
	v_readlane_b32 s0, v255, 26
	v_readlane_b32 s1, v255, 27
	v_readlane_b32 s78, v255, 29
	s_and_b64 s[0:1], s[70:71], s[0:1]
	v_readlane_b32 s79, v255, 30
	s_mov_b64 exec, s[0:1]
	s_cbranch_execz .LBB0_571
	v_readlane_b32 s0, v255, 22
	v_readlane_b32 s1, v255, 23
	v_add_f32_e32 v0, v52, v0
	s_nop 0
	v_lshl_add_u64 v[50:51], v[128:129], 3, s[0:1]
	global_atomic_add_f32 v[50:51], v0, off
	v_mov_b64_e32 v[50:51], 0
	s_branch .LBB0_571
